# previous best + LRU write-out waits count the other direction's store instead of draining it
# baseline (speedup 1.0000x reference)
.LBB0_405:
	s_or_b64 exec, exec, s[78:79]
	s_waitcnt lgkmcnt(2)
	v_cndmask_b32_e64 v16, v16, 1.0, s[26:27]
	s_waitcnt lgkmcnt(1)
	v_cndmask_b32_e64 v26, v17, 0, s[26:27]
	s_waitcnt lgkmcnt(0)
	v_fmac_f32_e32 v26, v16, v2
	ds_read2st64_b32 v[16:17], v190 offset0:100 offset1:101
	ds_read2st64_b32 v[18:19], v190 offset0:108 offset1:165
	ds_read2st64_b32 v[20:21], v190 offset0:166 offset1:167
	ds_read2st64_b32 v[22:23], v190 offset0:102 offset1:103
	ds_read2st64_b32 v[24:25], v190 offset0:104 offset1:105
	ds_read_b32 v2, v190 offset:44032
	s_waitcnt lgkmcnt(4)
	v_fma_f32 v16, v26, v16, v19
	ds_read2st64_b32 v[26:27], v190 offset0:168 offset1:169
	ds_read2st64_b32 v[28:29], v190 offset0:170 offset1:171
	ds_read2st64_b32 v[30:31], v190 offset0:106 offset1:107
	s_waitcnt lgkmcnt(6)
	v_fma_f32 v17, v16, v17, v20
	s_waitcnt lgkmcnt(5)
	v_fmac_f32_e32 v21, v17, v22
	ds_write2st64_b32 v190, v16, v17 offset0:165 offset1:166
	s_waitcnt lgkmcnt(3)
	v_fma_f32 v16, v21, v23, v26
	v_fmac_f32_e32 v27, v16, v24
	ds_write2st64_b32 v190, v21, v16 offset0:167 offset1:168
	s_waitcnt lgkmcnt(3)
	v_fma_f32 v16, v27, v25, v28
	s_waitcnt lgkmcnt(2)
	v_fmac_f32_e32 v29, v16, v30
	v_fmac_f32_e32 v2, v29, v31
	v_fma_f32 v0, v2, v18, v0
	v_fmac_f32_e32 v1, v0, v3
	ds_write2st64_b32 v190, v0, v1 offset0:173 offset1:174
	v_fma_f32 v0, v1, v4, v14
	v_fmac_f32_e32 v15, v5, v0
	ds_write2st64_b32 v190, v0, v15 offset0:175 offset1:176
	v_fma_f32 v0, v6, v15, v12
	v_fmac_f32_e32 v13, v7, v0
	ds_write2st64_b32 v190, v0, v13 offset0:177 offset1:178
	v_fma_f32 v0, v8, v13, v10
	v_fmac_f32_e32 v11, v9, v0
	ds_write2st64_b32 v190, v27, v16 offset0:169 offset1:170
	ds_write2st64_b32 v190, v29, v2 offset0:171 offset1:172
	ds_write2st64_b32 v190, v0, v11 offset0:179 offset1:180
	s_waitcnt lgkmcnt(0)
	s_barrier
	s_andn2_b64 vcc, exec, s[76:77]
	s_cbranch_vccnz .LBB0_411
	ds_read_b128 v[4:7], v193 offset:42240
	ds_read_b128 v[0:3], v193 offset:42256
	s_mov_b64 s[76:77], -1
	s_and_b64 vcc, exec, s[36:37]
	s_cbranch_vccz .LBB0_408
	s_waitcnt vmcnt(3)
	v_lshlrev_b32_e32 v8, 16, v112
	v_and_b32_e32 v9, 0xffff0000, v112
	v_mul_f32_e32 v10, 0xbfb8aa3b, v8
	v_mul_f32_e32 v11, 0xbfb8aa3b, v9
	v_exp_f32_e32 v10, v10
	v_exp_f32_e32 v11, v11
	s_waitcnt vmcnt(2)
	v_lshlrev_b32_e32 v12, 16, v108
	v_and_b32_e32 v13, 0xffff0000, v108
	v_add_f32_e32 v10, 1.0, v10
	v_add_f32_e32 v11, 1.0, v11
	v_rcp_f32_e32 v10, v10
	v_rcp_f32_e32 v11, v11
	s_waitcnt lgkmcnt(1)
	v_pk_add_f32 v[12:13], v[4:5], v[12:13]
	v_lshlrev_b32_e32 v14, 16, v109
	v_and_b32_e32 v15, 0xffff0000, v109
	v_pk_mul_f32 v[8:9], v[10:11], v[8:9]
	v_lshlrev_b32_e32 v10, 16, v113
	v_pk_mul_f32 v[8:9], v[8:9], v[12:13]
	v_and_b32_e32 v11, 0xffff0000, v113
	v_mul_f32_e32 v12, 0xbfb8aa3b, v10
	v_exp_f32_e32 v12, v12
	v_mul_f32_e32 v13, 0xbfb8aa3b, v11
	v_exp_f32_e32 v13, v13
	v_cvt_pk_bf16_f32 v8, v8, v9
	v_add_f32_e32 v9, 1.0, v12
	v_rcp_f32_e32 v12, v9
	v_add_f32_e32 v9, 1.0, v13
	v_rcp_f32_e32 v13, v9
	v_pk_add_f32 v[14:15], v[6:7], v[14:15]
	v_lshlrev_b32_e32 v16, 16, v111
	v_and_b32_e32 v17, 0xffff0000, v111
	v_pk_mul_f32 v[10:11], v[12:13], v[10:11]
	v_lshlrev_b32_e32 v12, 16, v114
	v_and_b32_e32 v13, 0xffff0000, v114
	v_mul_f32_e32 v9, 0xbfb8aa3b, v12
	v_pk_mul_f32 v[10:11], v[10:11], v[14:15]
	v_exp_f32_e32 v14, v9
	v_mul_f32_e32 v9, 0xbfb8aa3b, v13
	v_exp_f32_e32 v15, v9
	v_cvt_pk_bf16_f32 v9, v10, v11
	v_add_f32_e32 v10, 1.0, v14
	v_rcp_f32_e32 v10, v10
	v_add_f32_e32 v11, 1.0, v15
	v_rcp_f32_e32 v11, v11
	v_lshlrev_b32_e32 v14, 16, v110
	v_and_b32_e32 v15, 0xffff0000, v110
	s_waitcnt lgkmcnt(0)
	v_pk_add_f32 v[14:15], v[0:1], v[14:15]
	v_pk_mul_f32 v[10:11], v[10:11], v[12:13]
	v_lshlrev_b32_e32 v12, 16, v115
	v_pk_mul_f32 v[10:11], v[10:11], v[14:15]
	v_and_b32_e32 v13, 0xffff0000, v115
	v_mul_f32_e32 v14, 0xbfb8aa3b, v12
	v_exp_f32_e32 v14, v14
	v_mul_f32_e32 v15, 0xbfb8aa3b, v13
	v_exp_f32_e32 v15, v15
	v_cvt_pk_bf16_f32 v10, v10, v11
	v_add_f32_e32 v11, 1.0, v14
	v_rcp_f32_e32 v14, v11
	v_add_f32_e32 v11, 1.0, v15
	v_rcp_f32_e32 v15, v11
	v_pk_add_f32 v[16:17], v[2:3], v[16:17]
	s_mov_b64 s[76:77], 0
	v_pk_mul_f32 v[12:13], v[14:15], v[12:13]
	s_nop 0
	v_pk_mul_f32 v[12:13], v[12:13], v[16:17]

.LBB0_411:
	s_cmp_lt_i32 s80, 4
	s_cbranch_scc1 .LBB0_365
	ds_read_b128 v[4:7], v194
	ds_read_b128 v[0:3], v194 offset:16
	s_cmp_gt_u32 s80, 19
	s_mov_b64 s[36:37], -1
	s_cbranch_scc1 .LBB0_414
	s_waitcnt vmcnt(2)
	v_lshlrev_b32_e32 v8, 16, v104
	v_and_b32_e32 v9, 0xffff0000, v104
	v_mul_f32_e32 v10, 0xbfb8aa3b, v8
	v_mul_f32_e32 v11, 0xbfb8aa3b, v9
	v_exp_f32_e32 v10, v10
	v_exp_f32_e32 v11, v11
	s_waitcnt vmcnt(1)
	v_lshlrev_b32_e32 v12, 16, v100
	v_and_b32_e32 v13, 0xffff0000, v100
	v_add_f32_e32 v10, 1.0, v10
	v_add_f32_e32 v11, 1.0, v11
	v_rcp_f32_e32 v10, v10
	v_rcp_f32_e32 v11, v11
	s_waitcnt lgkmcnt(1)
	v_pk_add_f32 v[12:13], v[4:5], v[12:13]
	v_lshlrev_b32_e32 v14, 16, v101
	v_and_b32_e32 v15, 0xffff0000, v101
	v_pk_mul_f32 v[8:9], v[10:11], v[8:9]
	v_lshlrev_b32_e32 v10, 16, v105
	v_pk_mul_f32 v[8:9], v[8:9], v[12:13]
	v_and_b32_e32 v11, 0xffff0000, v105
	v_mul_f32_e32 v12, 0xbfb8aa3b, v10
	v_exp_f32_e32 v12, v12
	v_mul_f32_e32 v13, 0xbfb8aa3b, v11
	v_exp_f32_e32 v13, v13
	v_cvt_pk_bf16_f32 v8, v8, v9
	v_add_f32_e32 v9, 1.0, v12
	v_rcp_f32_e32 v12, v9
	v_add_f32_e32 v9, 1.0, v13
	v_rcp_f32_e32 v13, v9
	v_pk_add_f32 v[14:15], v[6:7], v[14:15]
	v_lshlrev_b32_e32 v16, 16, v103
	v_and_b32_e32 v17, 0xffff0000, v103
	v_pk_mul_f32 v[10:11], v[12:13], v[10:11]
	v_lshlrev_b32_e32 v12, 16, v106
	v_and_b32_e32 v13, 0xffff0000, v106
	v_mul_f32_e32 v9, 0xbfb8aa3b, v12
	v_pk_mul_f32 v[10:11], v[10:11], v[14:15]
	v_exp_f32_e32 v14, v9
	v_mul_f32_e32 v9, 0xbfb8aa3b, v13
	v_exp_f32_e32 v15, v9
	v_cvt_pk_bf16_f32 v9, v10, v11
	v_add_f32_e32 v10, 1.0, v14
	v_rcp_f32_e32 v10, v10
	v_add_f32_e32 v11, 1.0, v15
	v_rcp_f32_e32 v11, v11
	v_lshlrev_b32_e32 v14, 16, v102
	v_and_b32_e32 v15, 0xffff0000, v102
	s_waitcnt lgkmcnt(0)
	v_pk_add_f32 v[14:15], v[0:1], v[14:15]
	v_pk_mul_f32 v[10:11], v[10:11], v[12:13]
	v_lshlrev_b32_e32 v12, 16, v107
	v_pk_mul_f32 v[10:11], v[10:11], v[14:15]
	v_and_b32_e32 v13, 0xffff0000, v107
	v_mul_f32_e32 v14, 0xbfb8aa3b, v12
	v_exp_f32_e32 v14, v14
	v_mul_f32_e32 v15, 0xbfb8aa3b, v13
	v_exp_f32_e32 v15, v15
	v_cvt_pk_bf16_f32 v10, v10, v11
	v_add_f32_e32 v11, 1.0, v14
	v_rcp_f32_e32 v14, v11
	v_add_f32_e32 v11, 1.0, v15
	v_rcp_f32_e32 v15, v11
	v_pk_add_f32 v[16:17], v[2:3], v[16:17]
	s_mov_b64 s[36:37], 0
	v_pk_mul_f32 v[12:13], v[14:15], v[12:13]
	s_nop 0
	v_pk_mul_f32 v[12:13], v[12:13], v[16:17]
